# grid barrier: last cross-XCD arriver releases every XCC generation word directly (no per-XCD relay)
# speedup vs baseline: 1.0171x; 1.0039x over previous
.LBB0_1094:
	s_mov_b64 exec, -1
	s_mov_b32 s66, 0
	v_readlane_b32 s44, v251, 4
	v_readlane_b32 s45, v254, 42
	v_lshrrev_b32_e32 v4, 6, v178
	s_lshr_b32 s45, s45, 3
	v_readfirstlane_b32 s46, v4
	s_cmp_ge_i32 s44, 11
	s_cselect_b32 s47, 1, 0
	s_mul_i32 s48, s47, 10
	s_sub_i32 s48, s44, s48
	s_lshl_b32 s49, s47, 12
	s_and_b32 s54, s45, 1
	s_cmp_eq_u32 s54, s47
	s_cselect_b32 s54, 1, 0
	s_mov_b32 s50, 1
	s_mov_b32 s52, 0
	s_cmp_eq_u32 s48, 1
	s_cbranch_scc1 .Lsc_g1
	s_cmp_eq_u32 s48, 5
	s_cbranch_scc1 .Lsc_g2
	s_cmp_eq_u32 s48, 6
	s_cbranch_scc1 .Lsc_g3
	s_cmp_eq_u32 s48, 8
	s_cbranch_scc1 .Lsc_g4
	s_cmp_eq_u32 s48, 9
	s_cbranch_scc1 .Lsc_g5
	s_branch .Lsc_done

.Lsc_par:
	s_cmp_lt_i32 s55, 0
	s_cbranch_scc1 .Lsc_done
	s_cmp_eq_u32 s66, 0
	s_cbranch_scc1 .Lsc_nofl
	s_cmp_lt_u32 s45, 248
	s_cbranch_scc1 .Lsc_nofl
	s_cmp_lg_u32 s46, 0
	s_cbranch_scc1 .Lsc_nofl
	s_mov_b64 exec, 1
	buffer_wbl2 sc1
	s_mov_b64 exec, -1
.Lsc_nofl:
	s_cmp_eq_u32 s54, 0
	s_cbranch_scc1 .Lsc_done
	s_lshr_b32 s55, s55, 1
	s_lshl_b32 s55, s55, 3
	s_add_i32 s51, s51, s55

.LBB0_1131:
	s_or_b64 exec, exec, s[10:11]
	s_waitcnt vmcnt(0)
	v_readfirstlane_b32 s8, v3
	v_sub_u32_e32 v4, 0, v2
	s_mov_b64 s[10:11], -1
	v_add_u32_e32 v3, s8, v0
	v_cvt_f32_u32_e32 v0, v2
	v_readlane_b32 s8, v253, 32
	v_readlane_b32 s9, v253, 33
	v_rcp_iflag_f32_e32 v0, v0
	s_nop 0
	v_mul_f32_e32 v0, 0x4f7ffffe, v0
	v_cvt_u32_f32_e32 v0, v0
	v_mul_lo_u32 v4, v4, v0
	v_mul_hi_u32 v4, v0, v4
	v_add_u32_e32 v0, v0, v4
	v_mul_hi_u32 v0, v3, v0
	v_mul_lo_u32 v4, v0, v2
	v_sub_u32_e32 v4, v3, v4
	v_cmp_ge_u32_e32 vcc, v4, v2
	v_add_u32_e32 v5, 1, v0
	v_add_u32_e32 v3, 1, v3
	v_cndmask_b32_e32 v0, v0, v5, vcc
	v_sub_u32_e32 v5, v4, v2
	v_cndmask_b32_e32 v4, v4, v5, vcc
	v_cmp_ge_u32_e32 vcc, v4, v2
	v_add_u32_e32 v4, 1, v0
	s_nop 0
	v_cndmask_b32_e32 v0, v0, v4, vcc
	v_mul_lo_u32 v4, v2, v0
	v_add_u32_e32 v2, v4, v2
	v_cmp_ne_u32_e32 vcc, v3, v2
	v_mov_b64_e32 v[2:3], s[8:9]
	s_cmp_eq_u64 vcc, 0
	s_cselect_b32 s28, 1, 0
	s_and_saveexec_b64 s[8:9], vcc
	s_cbranch_execz .LBB0_1143
	v_readlane_b32 s10, v253, 32
	v_readlane_b32 s11, v253, 33
	s_mov_b64 s[12:13], 0
	s_nop 3
	global_load_dword v2, v1, s[10:11] sc1
	s_waitcnt vmcnt(0)
	v_cmp_eq_u32_e32 vcc, v2, v0
	s_and_saveexec_b64 s[10:11], vcc
	s_cbranch_execz .LBB0_1142
	s_mov_b32 s24, 1
	s_branch .LBB0_1135

.LBB0_1143:
	s_or_b64 exec, exec, s[8:9]
	s_cmp_eq_u32 s28, 1
	s_cbranch_scc0 .Lxg_skip
	v_readlane_b32 s12, v253, 28
	v_readlane_b32 s13, v253, 29
	s_getreg_b32 s14, hwreg(HW_REG_XCC_ID, 0, 4)
	s_lshl_b32 s14, s14, 8
	s_sub_u32 s12, s12, s14
	s_subb_u32 s13, s13, 0
	s_nop 4
	global_atomic_add v1, v183, s[12:13]
	global_atomic_add v1, v183, s[12:13] offset:256
	global_atomic_add v1, v183, s[12:13] offset:512
	global_atomic_add v1, v183, s[12:13] offset:768
	global_atomic_add v1, v183, s[12:13] offset:1024
	global_atomic_add v1, v183, s[12:13] offset:1280
	global_atomic_add v1, v183, s[12:13] offset:1536
	global_atomic_add v1, v183, s[12:13] offset:1792
	global_atomic_add v1, v183, s[12:13] offset:2048
	global_atomic_add v1, v183, s[12:13] offset:2304
	global_atomic_add v1, v183, s[12:13] offset:2560
	global_atomic_add v1, v183, s[12:13] offset:2816
	global_atomic_add v1, v183, s[12:13] offset:3072
	global_atomic_add v1, v183, s[12:13] offset:3328
	global_atomic_add v1, v183, s[12:13] offset:3584
	global_atomic_add v1, v183, s[12:13] offset:3840
.Lxg_skip:
	s_and_saveexec_b64 s[8:9], s[10:11]
	s_cbranch_execz .LBB0_1145
	global_atomic_add v[2:3], v183, off
.LBB0_1145:
	s_or_b64 exec, exec, s[8:9]
	s_mov_b64 s[8:9], exec
	v_mbcnt_lo_u32_b32 v0, s8, 0
	v_mbcnt_hi_u32_b32 v0, s9, v0
	v_cmp_eq_u32_e32 vcc, 0, v0
	s_waitcnt vmcnt(0)
	s_and_saveexec_b64 s[10:11], vcc
	s_cbranch_execz .LBB0_1147
	s_bcnt1_i32_b64 s8, s[8:9]
	v_mov_b32_e32 v0, s8
	v_readlane_b32 s8, v253, 28
	v_readlane_b32 s9, v253, 29
	s_nop 4
.LBB0_1147:
	s_or_b64 exec, exec, s[10:11]
	s_waitcnt vmcnt(0)
